# v23 + GEMM K loops: after the phase barrier the first MFMA issues before s_setprio 1 / the (redundant) lgkmcnt(0) wait
# baseline (speedup 1.0000x reference)
.LBB0_348:
	s_add_u32 s40, s22, 0xfffc0080
	s_addc_u32 s41, s23, -1
	s_add_i32 s71, 0, 0x10000
	s_cmp_eq_u32 s70, 12
	s_cselect_b32 s57, s14, s41
	s_cselect_b32 s56, s33, s40
	s_cselect_b32 s41, s27, s69
	s_cselect_b32 s40, s36, s49
	s_add_i32 s76, 0, 0x14000
	s_waitcnt lgkmcnt(0)
	v_add_u32_e32 v76, s71, v235
	v_add_u32_e32 v100, s76, v235
	ds_read_b128 v[64:67], v76
	ds_read_b128 v[68:71], v76 offset:1024
	ds_read_b128 v[72:75], v76 offset:2048
	ds_read_b128 v[76:79], v76 offset:3072
	ds_read_b128 v[84:87], v100
	ds_read_b128 v[88:91], v100 offset:1024
	ds_read_b128 v[96:99], v100 offset:2048
	ds_read_b128 v[100:103], v100 offset:3072
	v_lshl_add_u64 v[208:209], s[22:23], 0, v[202:203]
	s_add_i32 m0, s55, 0xc000
	ds_read_b128 v[160:163], v239
	ds_read_b128 v[164:167], v239 offset:1024
	ds_read_b128 v[168:171], v239 offset:2048
	ds_read_b128 v[172:175], v239 offset:3072
	ds_read_b128 v[176:179], v239 offset:4096
	ds_read_b128 v[180:183], v239 offset:5120
	ds_read_b128 v[184:187], v239 offset:6144
	ds_read_b128 v[204:207], v239 offset:7168
	global_load_lds_dwordx4 v[208:209], off
	v_lshl_add_u64 v[208:209], s[22:23], 0, v[200:201]
	s_add_i32 m0, s55, 0xe000
	s_nop 0
	global_load_lds_dwordx4 v[208:209], off
	s_waitcnt vmcnt(8)
	s_waitcnt lgkmcnt(0)
	s_barrier
	v_mfma_f32_16x16x32_bf16 v[156:159], v[64:67], v[160:163], v[156:159]
	s_setprio 1
	s_waitcnt lgkmcnt(0)
	v_mfma_f32_16x16x32_bf16 v[152:155], v[72:75], v[160:163], v[152:155]
	v_mfma_f32_16x16x32_bf16 v[140:143], v[64:67], v[168:171], v[140:143]
	v_mfma_f32_16x16x32_bf16 v[136:139], v[72:75], v[168:171], v[136:139]
	v_mfma_f32_16x16x32_bf16 v[124:127], v[64:67], v[176:179], v[124:127]
	v_mfma_f32_16x16x32_bf16 v[120:123], v[72:75], v[176:179], v[120:123]
	v_mfma_f32_16x16x32_bf16 v[108:111], v[64:67], v[184:187], v[108:111]
	v_mfma_f32_16x16x32_bf16 v[104:107], v[72:75], v[184:187], v[104:107]
	v_mfma_f32_16x16x32_bf16 v[156:159], v[68:71], v[164:167], v[156:159]
	v_mfma_f32_16x16x32_bf16 v[152:155], v[76:79], v[164:167], v[152:155]
	v_mfma_f32_16x16x32_bf16 v[140:143], v[68:71], v[172:175], v[140:143]
	v_mfma_f32_16x16x32_bf16 v[136:139], v[76:79], v[172:175], v[136:139]
	v_mfma_f32_16x16x32_bf16 v[124:127], v[68:71], v[180:183], v[124:127]
	v_mfma_f32_16x16x32_bf16 v[120:123], v[76:79], v[180:183], v[120:123]
	v_mfma_f32_16x16x32_bf16 v[108:111], v[68:71], v[204:207], v[108:111]
	v_mfma_f32_16x16x32_bf16 v[104:107], v[76:79], v[204:207], v[104:107]
	s_setprio 0
	s_setprio 1
	v_mfma_f32_16x16x32_bf16 v[148:151], v[84:87], v[160:163], v[148:151]
	v_mfma_f32_16x16x32_bf16 v[144:147], v[96:99], v[160:163], v[144:147]
	v_mfma_f32_16x16x32_bf16 v[132:135], v[84:87], v[168:171], v[132:135]
	v_mfma_f32_16x16x32_bf16 v[128:131], v[96:99], v[168:171], v[128:131]
	v_mfma_f32_16x16x32_bf16 v[116:119], v[84:87], v[176:179], v[116:119]
	v_mfma_f32_16x16x32_bf16 v[112:115], v[96:99], v[176:179], v[112:115]
	v_mfma_f32_16x16x32_bf16 v[92:95], v[84:87], v[184:187], v[92:95]
	v_mfma_f32_16x16x32_bf16 v[80:83], v[96:99], v[184:187], v[80:83]
	v_mfma_f32_16x16x32_bf16 v[148:151], v[88:91], v[164:167], v[148:151]
	v_mfma_f32_16x16x32_bf16 v[144:147], v[100:103], v[164:167], v[144:147]
	v_mfma_f32_16x16x32_bf16 v[132:135], v[88:91], v[172:175], v[132:135]
	v_mfma_f32_16x16x32_bf16 v[128:131], v[100:103], v[172:175], v[128:131]
	v_mfma_f32_16x16x32_bf16 v[116:119], v[88:91], v[180:183], v[116:119]
	v_mfma_f32_16x16x32_bf16 v[112:115], v[100:103], v[180:183], v[112:115]
	v_mfma_f32_16x16x32_bf16 v[92:95], v[88:91], v[204:207], v[92:95]
	v_mfma_f32_16x16x32_bf16 v[80:83], v[100:103], v[204:207], v[80:83]
	s_setprio 0
	s_barrier
	s_add_i32 s71, s71, s37
	v_lshl_add_u64 v[208:209], s[40:41], 0, v[188:189]
	s_mov_b32 m0, s71
	ds_read_b128 v[160:163], v239 offset:16384
	ds_read_b128 v[164:167], v239 offset:17408
	ds_read_b128 v[168:171], v239 offset:18432
	ds_read_b128 v[172:175], v239 offset:19456
	ds_read_b128 v[176:179], v239 offset:20480
	ds_read_b128 v[180:183], v239 offset:21504
	ds_read_b128 v[184:187], v239 offset:22528
	ds_read_b128 v[204:207], v239 offset:23552
	global_load_lds_dwordx4 v[208:209], off
	s_add_i32 m0, s71, 0x2000
	s_add_u32 s72, s40, 0x40000
	v_lshl_add_u64 v[210:211], s[40:41], 0, v[198:199]
	s_addc_u32 s73, s41, 0
	s_add_i32 s71, s76, s37
	global_load_lds_dwordx4 v[210:211], off
	v_lshl_add_u64 v[212:213], s[72:73], 0, v[188:189]
	s_mov_b32 m0, s71
	v_lshl_add_u64 v[214:215], s[56:57], 0, v[196:197]
	global_load_lds_dwordx4 v[212:213], off
	v_lshl_add_u64 v[212:213], s[72:73], 0, v[198:199]
	s_add_i32 m0, s71, 0x2000
	s_nop 0
	global_load_lds_dwordx4 v[212:213], off
	v_lshl_add_u64 v[212:213], s[56:57], 0, v[194:195]
	s_mov_b32 m0, s55
	s_nop 0
	global_load_lds_dwordx4 v[212:213], off
	s_mov_b32 m0, s60
	s_nop 0
	global_load_lds_dwordx4 v[214:215], off
	s_waitcnt vmcnt(8)
	s_waitcnt lgkmcnt(0)
	s_barrier
	v_mfma_f32_16x16x32_bf16 v[60:63], v[64:67], v[160:163], v[60:63]
	s_setprio 1
	s_waitcnt lgkmcnt(0)
	v_mfma_f32_16x16x32_bf16 v[56:59], v[72:75], v[160:163], v[56:59]
	v_mfma_f32_16x16x32_bf16 v[44:47], v[64:67], v[168:171], v[44:47]
	v_mfma_f32_16x16x32_bf16 v[40:43], v[72:75], v[168:171], v[40:43]
	v_mfma_f32_16x16x32_bf16 v[28:31], v[64:67], v[176:179], v[28:31]
	v_mfma_f32_16x16x32_bf16 v[24:27], v[72:75], v[176:179], v[24:27]
	v_mfma_f32_16x16x32_bf16 v[12:15], v[64:67], v[184:187], v[12:15]
	v_mfma_f32_16x16x32_bf16 v[8:11], v[72:75], v[184:187], v[8:11]
	v_mfma_f32_16x16x32_bf16 v[60:63], v[68:71], v[164:167], v[60:63]
	v_mfma_f32_16x16x32_bf16 v[56:59], v[76:79], v[164:167], v[56:59]
	v_mfma_f32_16x16x32_bf16 v[44:47], v[68:71], v[172:175], v[44:47]
	v_mfma_f32_16x16x32_bf16 v[40:43], v[76:79], v[172:175], v[40:43]
	v_mfma_f32_16x16x32_bf16 v[28:31], v[68:71], v[180:183], v[28:31]
	v_mfma_f32_16x16x32_bf16 v[24:27], v[76:79], v[180:183], v[24:27]
	v_mfma_f32_16x16x32_bf16 v[12:15], v[68:71], v[204:207], v[12:15]
	v_mfma_f32_16x16x32_bf16 v[8:11], v[76:79], v[204:207], v[8:11]
	s_setprio 0
	s_setprio 1
	v_mfma_f32_16x16x32_bf16 v[52:55], v[84:87], v[160:163], v[52:55]
	v_mfma_f32_16x16x32_bf16 v[48:51], v[96:99], v[160:163], v[48:51]
	v_mfma_f32_16x16x32_bf16 v[36:39], v[84:87], v[168:171], v[36:39]
	v_mfma_f32_16x16x32_bf16 v[32:35], v[96:99], v[168:171], v[32:35]
	v_mfma_f32_16x16x32_bf16 v[20:23], v[84:87], v[176:179], v[20:23]
	v_mfma_f32_16x16x32_bf16 v[16:19], v[96:99], v[176:179], v[16:19]
	v_mfma_f32_16x16x32_bf16 v[4:7], v[84:87], v[184:187], v[4:7]
	v_mfma_f32_16x16x32_bf16 v[0:3], v[96:99], v[184:187], v[0:3]
	v_mfma_f32_16x16x32_bf16 v[52:55], v[88:91], v[164:167], v[52:55]
	v_mfma_f32_16x16x32_bf16 v[48:51], v[100:103], v[164:167], v[48:51]
	v_mfma_f32_16x16x32_bf16 v[36:39], v[88:91], v[172:175], v[36:39]
	v_mfma_f32_16x16x32_bf16 v[32:35], v[100:103], v[172:175], v[32:35]
	v_mfma_f32_16x16x32_bf16 v[20:23], v[88:91], v[180:183], v[20:23]
	v_mfma_f32_16x16x32_bf16 v[16:19], v[100:103], v[180:183], v[16:19]
	v_mfma_f32_16x16x32_bf16 v[4:7], v[88:91], v[204:207], v[4:7]
	v_mfma_f32_16x16x32_bf16 v[0:3], v[100:103], v[204:207], v[0:3]
	s_setprio 0
	s_barrier
	s_add_i32 s71, 0, 0x18000
	s_add_i32 s72, 0, 0x1c000
	v_add_u32_e32 v76, s71, v235
	v_add_u32_e32 v100, s72, v235
	ds_read_b128 v[64:67], v76
	ds_read_b128 v[68:71], v76 offset:1024
	ds_read_b128 v[72:75], v76 offset:2048
	ds_read_b128 v[76:79], v76 offset:3072
	ds_read_b128 v[84:87], v100
	ds_read_b128 v[88:91], v100 offset:1024
	ds_read_b128 v[96:99], v100 offset:2048
	ds_read_b128 v[100:103], v100 offset:3072
	s_add_u32 s56, s56, 0x40000
	s_addc_u32 s57, s57, 0
	s_mov_b32 m0, s61
	v_lshl_add_u64 v[216:217], s[56:57], 0, v[194:195]
	ds_read_b128 v[160:163], v239 offset:32768
	ds_read_b128 v[164:167], v239 offset:33792
	ds_read_b128 v[168:171], v239 offset:34816
	ds_read_b128 v[172:175], v239 offset:35840
	ds_read_b128 v[176:179], v239 offset:36864
	ds_read_b128 v[180:183], v239 offset:37888
	ds_read_b128 v[184:187], v239 offset:38912
	ds_read_b128 v[204:207], v239 offset:39936
	global_load_lds_dwordx4 v[216:217], off
	v_lshl_add_u64 v[216:217], s[56:57], 0, v[196:197]
	s_mov_b32 m0, s62
	s_nop 0
	global_load_lds_dwordx4 v[216:217], off
	s_waitcnt vmcnt(8)
	s_waitcnt lgkmcnt(0)
	s_barrier
	v_mfma_f32_16x16x32_bf16 v[156:159], v[64:67], v[160:163], v[156:159]
	s_setprio 1
	s_waitcnt lgkmcnt(0)
	v_mfma_f32_16x16x32_bf16 v[152:155], v[72:75], v[160:163], v[152:155]
	v_mfma_f32_16x16x32_bf16 v[140:143], v[64:67], v[168:171], v[140:143]
	v_mfma_f32_16x16x32_bf16 v[136:139], v[72:75], v[168:171], v[136:139]
	v_mfma_f32_16x16x32_bf16 v[124:127], v[64:67], v[176:179], v[124:127]
	v_mfma_f32_16x16x32_bf16 v[120:123], v[72:75], v[176:179], v[120:123]
	v_mfma_f32_16x16x32_bf16 v[108:111], v[64:67], v[184:187], v[108:111]
	v_mfma_f32_16x16x32_bf16 v[104:107], v[72:75], v[184:187], v[104:107]
	v_mfma_f32_16x16x32_bf16 v[156:159], v[68:71], v[164:167], v[156:159]
	v_mfma_f32_16x16x32_bf16 v[152:155], v[76:79], v[164:167], v[152:155]
	v_mfma_f32_16x16x32_bf16 v[140:143], v[68:71], v[172:175], v[140:143]
	v_mfma_f32_16x16x32_bf16 v[136:139], v[76:79], v[172:175], v[136:139]
	v_mfma_f32_16x16x32_bf16 v[124:127], v[68:71], v[180:183], v[124:127]
	v_mfma_f32_16x16x32_bf16 v[120:123], v[76:79], v[180:183], v[120:123]
	v_mfma_f32_16x16x32_bf16 v[108:111], v[68:71], v[204:207], v[108:111]
	v_mfma_f32_16x16x32_bf16 v[104:107], v[76:79], v[204:207], v[104:107]
	s_setprio 0
	s_setprio 1
	v_mfma_f32_16x16x32_bf16 v[148:151], v[84:87], v[160:163], v[148:151]
	v_mfma_f32_16x16x32_bf16 v[144:147], v[96:99], v[160:163], v[144:147]
	v_mfma_f32_16x16x32_bf16 v[132:135], v[84:87], v[168:171], v[132:135]
	v_mfma_f32_16x16x32_bf16 v[128:131], v[96:99], v[168:171], v[128:131]
	v_mfma_f32_16x16x32_bf16 v[116:119], v[84:87], v[176:179], v[116:119]
	v_mfma_f32_16x16x32_bf16 v[112:115], v[96:99], v[176:179], v[112:115]
	v_mfma_f32_16x16x32_bf16 v[92:95], v[84:87], v[184:187], v[92:95]
	v_mfma_f32_16x16x32_bf16 v[80:83], v[96:99], v[184:187], v[80:83]
	v_mfma_f32_16x16x32_bf16 v[148:151], v[88:91], v[164:167], v[148:151]
	v_mfma_f32_16x16x32_bf16 v[144:147], v[100:103], v[164:167], v[144:147]
	v_mfma_f32_16x16x32_bf16 v[132:135], v[88:91], v[172:175], v[132:135]
	v_mfma_f32_16x16x32_bf16 v[128:131], v[100:103], v[172:175], v[128:131]
	v_mfma_f32_16x16x32_bf16 v[116:119], v[88:91], v[180:183], v[116:119]
	v_mfma_f32_16x16x32_bf16 v[112:115], v[100:103], v[180:183], v[112:115]
	v_mfma_f32_16x16x32_bf16 v[92:95], v[88:91], v[204:207], v[92:95]
	v_mfma_f32_16x16x32_bf16 v[80:83], v[100:103], v[204:207], v[80:83]
	s_setprio 0
	s_barrier
	s_add_i32 s56, s71, s37
	v_lshl_add_u64 v[208:209], v[208:209], 0, s[30:31]
	s_mov_b32 m0, s56
	ds_read_b128 v[160:163], v239 offset:49152
	ds_read_b128 v[164:167], v239 offset:50176
	ds_read_b128 v[168:171], v239 offset:51200
	ds_read_b128 v[172:175], v239 offset:52224
	ds_read_b128 v[176:179], v239 offset:53248
	ds_read_b128 v[180:183], v239 offset:54272
	ds_read_b128 v[184:187], v239 offset:55296
	ds_read_b128 v[204:207], v239 offset:56320
	global_load_lds_dwordx4 v[208:209], off
	s_add_i32 m0, s56, 0x2000
	s_add_u32 s40, s40, 0x40080
	v_lshl_add_u64 v[208:209], v[210:211], 0, s[30:31]
	s_addc_u32 s41, s41, 0
	s_add_i32 s56, s72, s37
	global_load_lds_dwordx4 v[208:209], off
	v_lshl_add_u64 v[208:209], s[40:41], 0, v[188:189]
	s_mov_b32 m0, s56
	s_nop 0
	global_load_lds_dwordx4 v[208:209], off
	v_lshl_add_u64 v[208:209], s[40:41], 0, v[198:199]
	s_add_i32 m0, s56, 0x2000
	s_nop 0
	global_load_lds_dwordx4 v[208:209], off
	v_lshl_add_u64 v[208:209], v[212:213], 0, s[30:31]
	s_mov_b32 m0, s64
	s_nop 0
	global_load_lds_dwordx4 v[208:209], off
	v_lshl_add_u64 v[208:209], v[214:215], 0, s[30:31]
	s_mov_b32 m0, s65
	s_nop 0
	global_load_lds_dwordx4 v[208:209], off
	s_waitcnt vmcnt(8)
	s_waitcnt lgkmcnt(0)
	s_barrier
	v_mfma_f32_16x16x32_bf16 v[60:63], v[64:67], v[160:163], v[60:63]
	s_setprio 1
	s_waitcnt lgkmcnt(0)
	v_mfma_f32_16x16x32_bf16 v[56:59], v[72:75], v[160:163], v[56:59]
	v_mfma_f32_16x16x32_bf16 v[44:47], v[64:67], v[168:171], v[44:47]
	v_mfma_f32_16x16x32_bf16 v[40:43], v[72:75], v[168:171], v[40:43]
	v_mfma_f32_16x16x32_bf16 v[28:31], v[64:67], v[176:179], v[28:31]
	v_mfma_f32_16x16x32_bf16 v[24:27], v[72:75], v[176:179], v[24:27]
	v_mfma_f32_16x16x32_bf16 v[12:15], v[64:67], v[184:187], v[12:15]
	v_mfma_f32_16x16x32_bf16 v[8:11], v[72:75], v[184:187], v[8:11]
	v_mfma_f32_16x16x32_bf16 v[60:63], v[68:71], v[164:167], v[60:63]
	v_mfma_f32_16x16x32_bf16 v[56:59], v[76:79], v[164:167], v[56:59]
	v_mfma_f32_16x16x32_bf16 v[44:47], v[68:71], v[172:175], v[44:47]
	v_mfma_f32_16x16x32_bf16 v[40:43], v[76:79], v[172:175], v[40:43]
	v_mfma_f32_16x16x32_bf16 v[28:31], v[68:71], v[180:183], v[28:31]
	v_mfma_f32_16x16x32_bf16 v[24:27], v[76:79], v[180:183], v[24:27]
	v_mfma_f32_16x16x32_bf16 v[12:15], v[68:71], v[204:207], v[12:15]
	v_mfma_f32_16x16x32_bf16 v[8:11], v[76:79], v[204:207], v[8:11]
	s_setprio 0
	s_setprio 1
	v_mfma_f32_16x16x32_bf16 v[52:55], v[84:87], v[160:163], v[52:55]
	v_mfma_f32_16x16x32_bf16 v[48:51], v[96:99], v[160:163], v[48:51]
	v_mfma_f32_16x16x32_bf16 v[36:39], v[84:87], v[168:171], v[36:39]
	v_mfma_f32_16x16x32_bf16 v[32:35], v[96:99], v[168:171], v[32:35]
	v_mfma_f32_16x16x32_bf16 v[20:23], v[84:87], v[176:179], v[20:23]
	v_mfma_f32_16x16x32_bf16 v[16:19], v[96:99], v[176:179], v[16:19]
	v_mfma_f32_16x16x32_bf16 v[4:7], v[84:87], v[184:187], v[4:7]
	v_mfma_f32_16x16x32_bf16 v[0:3], v[96:99], v[184:187], v[0:3]
	v_mfma_f32_16x16x32_bf16 v[52:55], v[88:91], v[164:167], v[52:55]
	v_mfma_f32_16x16x32_bf16 v[48:51], v[100:103], v[164:167], v[48:51]
	v_mfma_f32_16x16x32_bf16 v[36:39], v[88:91], v[172:175], v[36:39]
	v_mfma_f32_16x16x32_bf16 v[32:35], v[100:103], v[172:175], v[32:35]
	v_mfma_f32_16x16x32_bf16 v[20:23], v[88:91], v[180:183], v[20:23]
	v_mfma_f32_16x16x32_bf16 v[16:19], v[100:103], v[180:183], v[16:19]
	v_mfma_f32_16x16x32_bf16 v[4:7], v[88:91], v[204:207], v[4:7]
	v_mfma_f32_16x16x32_bf16 v[0:3], v[100:103], v[204:207], v[0:3]
	s_setprio 0
	s_barrier
	s_add_i32 s70, s70, 2
	s_add_u32 s49, s49, 0x100
	s_addc_u32 s69, s69, 0
	s_add_u32 s22, s22, 0x100
	s_addc_u32 s23, s23, 0
	s_cmp_gt_u32 s70, 13
	s_cbranch_scc0 .LBB0_348
	s_and_b64 vcc, exec, s[42:43]
	s_cbranch_vccz .LBB0_351
	s_barrier

.LBB0_508:
	s_add_u32 s22, s12, 0xfffc0080
	s_addc_u32 s23, s13, -1
	s_add_i32 s76, 0, 0x10000
	s_cmp_eq_u32 s86, 12
	s_cselect_b32 s51, s33, s23
	s_cselect_b32 s50, s39, s22
	s_cselect_b32 s23, s35, s85
	s_cselect_b32 s22, s41, s49
	s_add_i32 s77, 0, 0x14000
	v_add_u32_e32 v140, s76, v155
	v_add_u32_e32 v174, s77, v155
	ds_read_b128 v[128:131], v140
	ds_read_b128 v[132:135], v140 offset:1024
	ds_read_b128 v[136:139], v140 offset:2048
	ds_read_b128 v[140:143], v140 offset:3072
	ds_read_b128 v[162:165], v174
	ds_read_b128 v[166:169], v174 offset:1024
	ds_read_b128 v[170:173], v174 offset:2048
	ds_read_b128 v[174:177], v174 offset:3072
	v_lshl_add_u64 v[186:187], s[12:13], 0, v[160:161]
	s_add_i32 m0, s58, 0xc000
	ds_read_b128 v[178:181], v205
	ds_read_b128 v[182:185], v205 offset:1024
	ds_read_b128 v[194:197], v205 offset:2048
	ds_read_b128 v[198:201], v205 offset:3072
	ds_read_b128 v[206:209], v205 offset:4096
	ds_read_b128 v[210:213], v205 offset:5120
	ds_read_b128 v[214:217], v205 offset:6144
	ds_read_b128 v[218:221], v205 offset:7168
	global_load_lds_dwordx4 v[186:187], off
	v_lshl_add_u64 v[186:187], s[12:13], 0, v[158:159]
	s_add_i32 m0, s58, 0xe000
	s_nop 0
	global_load_lds_dwordx4 v[186:187], off
	s_waitcnt vmcnt(8)
	s_waitcnt lgkmcnt(0)
	s_barrier
	v_mfma_f32_16x16x32_bf16 v[124:127], v[128:131], v[178:181], v[124:127]
	s_setprio 1
	s_waitcnt lgkmcnt(0)
	v_mfma_f32_16x16x32_bf16 v[120:123], v[136:139], v[178:181], v[120:123]
	v_mfma_f32_16x16x32_bf16 v[108:111], v[128:131], v[194:197], v[108:111]
	v_mfma_f32_16x16x32_bf16 v[104:107], v[136:139], v[194:197], v[104:107]
	v_mfma_f32_16x16x32_bf16 v[92:95], v[128:131], v[206:209], v[92:95]
	v_mfma_f32_16x16x32_bf16 v[88:91], v[136:139], v[206:209], v[88:91]
	v_mfma_f32_16x16x32_bf16 v[76:79], v[128:131], v[214:217], v[76:79]
	v_mfma_f32_16x16x32_bf16 v[72:75], v[136:139], v[214:217], v[72:75]
	v_mfma_f32_16x16x32_bf16 v[124:127], v[132:135], v[182:185], v[124:127]
	v_mfma_f32_16x16x32_bf16 v[120:123], v[140:143], v[182:185], v[120:123]
	v_mfma_f32_16x16x32_bf16 v[108:111], v[132:135], v[198:201], v[108:111]
	v_mfma_f32_16x16x32_bf16 v[104:107], v[140:143], v[198:201], v[104:107]
	v_mfma_f32_16x16x32_bf16 v[92:95], v[132:135], v[210:213], v[92:95]
	v_mfma_f32_16x16x32_bf16 v[88:91], v[140:143], v[210:213], v[88:91]
	v_mfma_f32_16x16x32_bf16 v[76:79], v[132:135], v[218:221], v[76:79]
	v_mfma_f32_16x16x32_bf16 v[72:75], v[140:143], v[218:221], v[72:75]
	s_setprio 0
	s_setprio 1
	v_mfma_f32_16x16x32_bf16 v[116:119], v[162:165], v[178:181], v[116:119]
	v_mfma_f32_16x16x32_bf16 v[112:115], v[170:173], v[178:181], v[112:115]
	v_mfma_f32_16x16x32_bf16 v[100:103], v[162:165], v[194:197], v[100:103]
	v_mfma_f32_16x16x32_bf16 v[96:99], v[170:173], v[194:197], v[96:99]
	v_mfma_f32_16x16x32_bf16 v[84:87], v[162:165], v[206:209], v[84:87]
	v_mfma_f32_16x16x32_bf16 v[80:83], v[170:173], v[206:209], v[80:83]
	v_mfma_f32_16x16x32_bf16 v[68:71], v[162:165], v[214:217], v[68:71]
	v_mfma_f32_16x16x32_bf16 v[64:67], v[170:173], v[214:217], v[64:67]
	v_mfma_f32_16x16x32_bf16 v[116:119], v[166:169], v[182:185], v[116:119]
	v_mfma_f32_16x16x32_bf16 v[112:115], v[174:177], v[182:185], v[112:115]
	v_mfma_f32_16x16x32_bf16 v[100:103], v[166:169], v[198:201], v[100:103]
	v_mfma_f32_16x16x32_bf16 v[96:99], v[174:177], v[198:201], v[96:99]
	v_mfma_f32_16x16x32_bf16 v[84:87], v[166:169], v[210:213], v[84:87]
	v_mfma_f32_16x16x32_bf16 v[80:83], v[174:177], v[210:213], v[80:83]
	v_mfma_f32_16x16x32_bf16 v[68:71], v[166:169], v[218:221], v[68:71]
	v_mfma_f32_16x16x32_bf16 v[64:67], v[174:177], v[218:221], v[64:67]
	s_setprio 0
	s_barrier
	s_add_i32 s76, s76, s57
	v_lshl_add_u64 v[186:187], s[22:23], 0, v[146:147]
	s_mov_b32 m0, s76
	ds_read_b128 v[178:181], v205 offset:16384
	ds_read_b128 v[182:185], v205 offset:17408
	ds_read_b128 v[194:197], v205 offset:18432
	ds_read_b128 v[198:201], v205 offset:19456
	ds_read_b128 v[206:209], v205 offset:20480
	ds_read_b128 v[210:213], v205 offset:21504
	ds_read_b128 v[214:217], v205 offset:22528
	ds_read_b128 v[218:221], v205 offset:23552
	global_load_lds_dwordx4 v[186:187], off
	s_add_i32 m0, s76, 0x2000
	s_add_u32 s90, s22, 0x40000
	v_lshl_add_u64 v[222:223], s[22:23], 0, v[150:151]
	s_addc_u32 s91, s23, 0
	s_add_i32 s76, s77, s57
	global_load_lds_dwordx4 v[222:223], off
	v_lshl_add_u64 v[224:225], s[90:91], 0, v[146:147]
	s_mov_b32 m0, s76
	v_lshl_add_u64 v[226:227], s[50:51], 0, v[148:149]
	global_load_lds_dwordx4 v[224:225], off
	v_lshl_add_u64 v[224:225], s[90:91], 0, v[150:151]
	s_add_i32 m0, s76, 0x2000
	s_nop 0
	global_load_lds_dwordx4 v[224:225], off
	v_lshl_add_u64 v[224:225], s[50:51], 0, v[144:145]
	s_mov_b32 m0, s58
	s_nop 0
	global_load_lds_dwordx4 v[224:225], off
	s_mov_b32 m0, s59
	s_nop 0
	global_load_lds_dwordx4 v[226:227], off
	s_waitcnt vmcnt(8)
	s_waitcnt lgkmcnt(0)
	s_barrier
	v_mfma_f32_16x16x32_bf16 v[60:63], v[128:131], v[178:181], v[60:63]
	s_setprio 1
	s_waitcnt lgkmcnt(0)
	v_mfma_f32_16x16x32_bf16 v[56:59], v[136:139], v[178:181], v[56:59]
	v_mfma_f32_16x16x32_bf16 v[44:47], v[128:131], v[194:197], v[44:47]
	v_mfma_f32_16x16x32_bf16 v[40:43], v[136:139], v[194:197], v[40:43]
	v_mfma_f32_16x16x32_bf16 v[28:31], v[128:131], v[206:209], v[28:31]
	v_mfma_f32_16x16x32_bf16 v[24:27], v[136:139], v[206:209], v[24:27]
	v_mfma_f32_16x16x32_bf16 v[12:15], v[128:131], v[214:217], v[12:15]
	v_mfma_f32_16x16x32_bf16 v[8:11], v[136:139], v[214:217], v[8:11]
	v_mfma_f32_16x16x32_bf16 v[60:63], v[132:135], v[182:185], v[60:63]
	v_mfma_f32_16x16x32_bf16 v[56:59], v[140:143], v[182:185], v[56:59]
	v_mfma_f32_16x16x32_bf16 v[44:47], v[132:135], v[198:201], v[44:47]
	v_mfma_f32_16x16x32_bf16 v[40:43], v[140:143], v[198:201], v[40:43]
	v_mfma_f32_16x16x32_bf16 v[28:31], v[132:135], v[210:213], v[28:31]
	v_mfma_f32_16x16x32_bf16 v[24:27], v[140:143], v[210:213], v[24:27]
	v_mfma_f32_16x16x32_bf16 v[12:15], v[132:135], v[218:221], v[12:15]
	v_mfma_f32_16x16x32_bf16 v[8:11], v[140:143], v[218:221], v[8:11]
	s_setprio 0
	s_setprio 1
	v_mfma_f32_16x16x32_bf16 v[52:55], v[162:165], v[178:181], v[52:55]
	v_mfma_f32_16x16x32_bf16 v[48:51], v[170:173], v[178:181], v[48:51]
	v_mfma_f32_16x16x32_bf16 v[36:39], v[162:165], v[194:197], v[36:39]
	v_mfma_f32_16x16x32_bf16 v[32:35], v[170:173], v[194:197], v[32:35]
	v_mfma_f32_16x16x32_bf16 v[20:23], v[162:165], v[206:209], v[20:23]
	v_mfma_f32_16x16x32_bf16 v[16:19], v[170:173], v[206:209], v[16:19]
	v_mfma_f32_16x16x32_bf16 v[4:7], v[162:165], v[214:217], v[4:7]
	v_mfma_f32_16x16x32_bf16 v[0:3], v[170:173], v[214:217], v[0:3]
	v_mfma_f32_16x16x32_bf16 v[52:55], v[166:169], v[182:185], v[52:55]
	v_mfma_f32_16x16x32_bf16 v[48:51], v[174:177], v[182:185], v[48:51]
	v_mfma_f32_16x16x32_bf16 v[36:39], v[166:169], v[198:201], v[36:39]
	v_mfma_f32_16x16x32_bf16 v[32:35], v[174:177], v[198:201], v[32:35]
	v_mfma_f32_16x16x32_bf16 v[20:23], v[166:169], v[210:213], v[20:23]
	v_mfma_f32_16x16x32_bf16 v[16:19], v[174:177], v[210:213], v[16:19]
	v_mfma_f32_16x16x32_bf16 v[4:7], v[166:169], v[218:221], v[4:7]
	v_mfma_f32_16x16x32_bf16 v[0:3], v[174:177], v[218:221], v[0:3]
	s_setprio 0
	s_barrier
	s_add_i32 s76, 0, 0x18000
	s_add_i32 s77, 0, 0x1c000
	v_add_u32_e32 v140, s76, v155
	v_add_u32_e32 v174, s77, v155
	ds_read_b128 v[128:131], v140
	ds_read_b128 v[132:135], v140 offset:1024
	ds_read_b128 v[136:139], v140 offset:2048
	ds_read_b128 v[140:143], v140 offset:3072
	ds_read_b128 v[162:165], v174
	ds_read_b128 v[166:169], v174 offset:1024
	ds_read_b128 v[170:173], v174 offset:2048
	ds_read_b128 v[174:177], v174 offset:3072
	s_add_u32 s50, s50, 0x40000
	s_addc_u32 s51, s51, 0
	s_mov_b32 m0, s60
	v_lshl_add_u64 v[234:235], s[50:51], 0, v[144:145]
	ds_read_b128 v[178:181], v205 offset:32768
	ds_read_b128 v[182:185], v205 offset:33792
	ds_read_b128 v[194:197], v205 offset:34816
	ds_read_b128 v[198:201], v205 offset:35840
	ds_read_b128 v[206:209], v205 offset:36864
	ds_read_b128 v[210:213], v205 offset:37888
	ds_read_b128 v[214:217], v205 offset:38912
	ds_read_b128 v[218:221], v205 offset:39936
	global_load_lds_dwordx4 v[234:235], off
	v_lshl_add_u64 v[234:235], s[50:51], 0, v[148:149]
	s_mov_b32 m0, s61
	s_nop 0
	global_load_lds_dwordx4 v[234:235], off
	s_waitcnt vmcnt(8)
	s_waitcnt lgkmcnt(0)
	s_barrier
	v_mfma_f32_16x16x32_bf16 v[124:127], v[128:131], v[178:181], v[124:127]
	s_setprio 1
	s_waitcnt lgkmcnt(0)
	v_mfma_f32_16x16x32_bf16 v[120:123], v[136:139], v[178:181], v[120:123]
	v_mfma_f32_16x16x32_bf16 v[108:111], v[128:131], v[194:197], v[108:111]
	v_mfma_f32_16x16x32_bf16 v[104:107], v[136:139], v[194:197], v[104:107]
	v_mfma_f32_16x16x32_bf16 v[92:95], v[128:131], v[206:209], v[92:95]
	v_mfma_f32_16x16x32_bf16 v[88:91], v[136:139], v[206:209], v[88:91]
	v_mfma_f32_16x16x32_bf16 v[76:79], v[128:131], v[214:217], v[76:79]
	v_mfma_f32_16x16x32_bf16 v[72:75], v[136:139], v[214:217], v[72:75]
	v_mfma_f32_16x16x32_bf16 v[124:127], v[132:135], v[182:185], v[124:127]
	v_mfma_f32_16x16x32_bf16 v[120:123], v[140:143], v[182:185], v[120:123]
	v_mfma_f32_16x16x32_bf16 v[108:111], v[132:135], v[198:201], v[108:111]
	v_mfma_f32_16x16x32_bf16 v[104:107], v[140:143], v[198:201], v[104:107]
	v_mfma_f32_16x16x32_bf16 v[92:95], v[132:135], v[210:213], v[92:95]
	v_mfma_f32_16x16x32_bf16 v[88:91], v[140:143], v[210:213], v[88:91]
	v_mfma_f32_16x16x32_bf16 v[76:79], v[132:135], v[218:221], v[76:79]
	v_mfma_f32_16x16x32_bf16 v[72:75], v[140:143], v[218:221], v[72:75]
	s_setprio 0
	s_setprio 1
	v_mfma_f32_16x16x32_bf16 v[116:119], v[162:165], v[178:181], v[116:119]
	v_mfma_f32_16x16x32_bf16 v[112:115], v[170:173], v[178:181], v[112:115]
	v_mfma_f32_16x16x32_bf16 v[100:103], v[162:165], v[194:197], v[100:103]
	v_mfma_f32_16x16x32_bf16 v[96:99], v[170:173], v[194:197], v[96:99]
	v_mfma_f32_16x16x32_bf16 v[84:87], v[162:165], v[206:209], v[84:87]
	v_mfma_f32_16x16x32_bf16 v[80:83], v[170:173], v[206:209], v[80:83]
	v_mfma_f32_16x16x32_bf16 v[68:71], v[162:165], v[214:217], v[68:71]
	v_mfma_f32_16x16x32_bf16 v[64:67], v[170:173], v[214:217], v[64:67]
	v_mfma_f32_16x16x32_bf16 v[116:119], v[166:169], v[182:185], v[116:119]
	v_mfma_f32_16x16x32_bf16 v[112:115], v[174:177], v[182:185], v[112:115]
	v_mfma_f32_16x16x32_bf16 v[100:103], v[166:169], v[198:201], v[100:103]
	v_mfma_f32_16x16x32_bf16 v[96:99], v[174:177], v[198:201], v[96:99]
	v_mfma_f32_16x16x32_bf16 v[84:87], v[166:169], v[210:213], v[84:87]
	v_mfma_f32_16x16x32_bf16 v[80:83], v[174:177], v[210:213], v[80:83]
	v_mfma_f32_16x16x32_bf16 v[68:71], v[166:169], v[218:221], v[68:71]
	v_mfma_f32_16x16x32_bf16 v[64:67], v[174:177], v[218:221], v[64:67]
	s_setprio 0
	s_barrier
	s_add_i32 s50, s76, s57
	v_lshl_add_u64 v[186:187], v[186:187], 0, s[30:31]
	s_mov_b32 m0, s50
	ds_read_b128 v[178:181], v205 offset:49152
	ds_read_b128 v[182:185], v205 offset:50176
	ds_read_b128 v[194:197], v205 offset:51200
	ds_read_b128 v[198:201], v205 offset:52224
	ds_read_b128 v[206:209], v205 offset:53248
	ds_read_b128 v[210:213], v205 offset:54272
	ds_read_b128 v[214:217], v205 offset:55296
	ds_read_b128 v[218:221], v205 offset:56320
	global_load_lds_dwordx4 v[186:187], off
	s_add_i32 m0, s50, 0x2000
	s_add_u32 s22, s22, 0x40080
	v_lshl_add_u64 v[186:187], v[222:223], 0, s[30:31]
	s_addc_u32 s23, s23, 0
	s_add_i32 s50, s77, s57
	global_load_lds_dwordx4 v[186:187], off
	v_lshl_add_u64 v[186:187], s[22:23], 0, v[146:147]
	s_mov_b32 m0, s50
	s_nop 0
	global_load_lds_dwordx4 v[186:187], off
	v_lshl_add_u64 v[186:187], s[22:23], 0, v[150:151]
	s_add_i32 m0, s50, 0x2000
	s_nop 0
	global_load_lds_dwordx4 v[186:187], off
	v_lshl_add_u64 v[186:187], v[224:225], 0, s[30:31]
	s_mov_b32 m0, s65
	s_nop 0
	global_load_lds_dwordx4 v[186:187], off
	v_lshl_add_u64 v[186:187], v[226:227], 0, s[30:31]
	s_mov_b32 m0, s66
	s_nop 0
	global_load_lds_dwordx4 v[186:187], off
	s_waitcnt vmcnt(8)
	s_waitcnt lgkmcnt(0)
	s_barrier
	v_mfma_f32_16x16x32_bf16 v[60:63], v[128:131], v[178:181], v[60:63]
	s_setprio 1
	s_waitcnt lgkmcnt(0)
	v_mfma_f32_16x16x32_bf16 v[56:59], v[136:139], v[178:181], v[56:59]
	v_mfma_f32_16x16x32_bf16 v[44:47], v[128:131], v[194:197], v[44:47]
	v_mfma_f32_16x16x32_bf16 v[40:43], v[136:139], v[194:197], v[40:43]
	v_mfma_f32_16x16x32_bf16 v[28:31], v[128:131], v[206:209], v[28:31]
	v_mfma_f32_16x16x32_bf16 v[24:27], v[136:139], v[206:209], v[24:27]
	v_mfma_f32_16x16x32_bf16 v[12:15], v[128:131], v[214:217], v[12:15]
	v_mfma_f32_16x16x32_bf16 v[8:11], v[136:139], v[214:217], v[8:11]
	v_mfma_f32_16x16x32_bf16 v[60:63], v[132:135], v[182:185], v[60:63]
	v_mfma_f32_16x16x32_bf16 v[56:59], v[140:143], v[182:185], v[56:59]
	v_mfma_f32_16x16x32_bf16 v[44:47], v[132:135], v[198:201], v[44:47]
	v_mfma_f32_16x16x32_bf16 v[40:43], v[140:143], v[198:201], v[40:43]
	v_mfma_f32_16x16x32_bf16 v[28:31], v[132:135], v[210:213], v[28:31]
	v_mfma_f32_16x16x32_bf16 v[24:27], v[140:143], v[210:213], v[24:27]
	v_mfma_f32_16x16x32_bf16 v[12:15], v[132:135], v[218:221], v[12:15]
	v_mfma_f32_16x16x32_bf16 v[8:11], v[140:143], v[218:221], v[8:11]
	s_setprio 0
	s_setprio 1
	v_mfma_f32_16x16x32_bf16 v[52:55], v[162:165], v[178:181], v[52:55]
	v_mfma_f32_16x16x32_bf16 v[48:51], v[170:173], v[178:181], v[48:51]
	v_mfma_f32_16x16x32_bf16 v[36:39], v[162:165], v[194:197], v[36:39]
	v_mfma_f32_16x16x32_bf16 v[32:35], v[170:173], v[194:197], v[32:35]
	v_mfma_f32_16x16x32_bf16 v[20:23], v[162:165], v[206:209], v[20:23]
	v_mfma_f32_16x16x32_bf16 v[16:19], v[170:173], v[206:209], v[16:19]
	v_mfma_f32_16x16x32_bf16 v[4:7], v[162:165], v[214:217], v[4:7]
	v_mfma_f32_16x16x32_bf16 v[0:3], v[170:173], v[214:217], v[0:3]
	v_mfma_f32_16x16x32_bf16 v[52:55], v[166:169], v[182:185], v[52:55]
	v_mfma_f32_16x16x32_bf16 v[48:51], v[174:177], v[182:185], v[48:51]
	v_mfma_f32_16x16x32_bf16 v[36:39], v[166:169], v[198:201], v[36:39]
	v_mfma_f32_16x16x32_bf16 v[32:35], v[174:177], v[198:201], v[32:35]
	v_mfma_f32_16x16x32_bf16 v[20:23], v[166:169], v[210:213], v[20:23]
	v_mfma_f32_16x16x32_bf16 v[16:19], v[174:177], v[210:213], v[16:19]
	v_mfma_f32_16x16x32_bf16 v[4:7], v[166:169], v[218:221], v[4:7]
	v_mfma_f32_16x16x32_bf16 v[0:3], v[174:177], v[218:221], v[0:3]
	s_setprio 0
	s_barrier
	s_add_i32 s86, s86, 2
	s_add_u32 s49, s49, 0x100
	s_addc_u32 s85, s85, 0
	s_add_u32 s12, s12, 0x100
	s_addc_u32 s13, s13, 0
	s_cmp_gt_u32 s86, 13
	s_cbranch_scc0 .LBB0_508
	s_and_b64 vcc, exec, s[26:27]
	s_cbranch_vccz .LBB0_511
	s_barrier
